# as v67 with s_setprio 1 on the four scanner waves for the duration of the scan loop (same code placement mod 128)
# baseline (speedup 1.0000x reference)
; __device__ __forceinline__ void rwkv_scan_phase(Frame& F, const bf16* RKV, const float* WAG, const bf16* AGB, const float* k_k, const float* k_a, const float* r_k, bf16* Y, float* BS, float* ST2) {
;     ...
;         } else {
;             const int row = lane >> 3, kg = lane & 7, vr = 8 * wave + row;
;             typedef float f32x2 __attribute__((ext_vector_type(2)));
;             f32x2 s[4];
; #pragma unroll
;             for (int i = 0; i < 4; ++i) s[i] = (f32x2){0.f, 0.f};
;             __syncthreads();
;             for (int ci = 0; ci < SEQ / SC_T; ++ci) {
.LBB0_1689:
	s_andn2_b64 vcc, exec, s[22:23]
	s_mov_b64 s[6:7], -1
	s_waitcnt vmcnt(16)
	s_barrier
	s_cbranch_vccnz .LBB0_1756
	s_setprio 1
	v_mov_b32_e32 v8, 0
	s_mov_b32 s0, 0
	v_mov_b32_e32 v9, v8
	v_mov_b32_e32 v10, v8
	v_mov_b32_e32 v11, v8
	s_waitcnt vmcnt(7)
	v_mov_b32_e32 v20, v8
	v_mov_b32_e32 v21, v8
	v_mov_b32_e32 v22, v8
	v_mov_b32_e32 v23, v8
	s_barrier
	s_branch .LBB0_1692

; __device__ __forceinline__ void rwkv_scan_phase(Frame& F, const bf16* RKV, const float* WAG, const bf16* AGB, const float* k_k, const float* k_a, const float* r_k, bf16* Y, float* BS, float* ST2) {
;     ...
;                 __syncthreads();
;             }
;         }
;     }
.LBB0_1757:
	s_setprio 0
	s_nop 0
	s_nop 0
	s_nop 0
	s_nop 0
	s_nop 0
	s_nop 0
	s_nop 0
	s_nop 0
	s_nop 0
	s_nop 0
	s_nop 0
	s_nop 0
	s_nop 0
	s_nop 0
	s_nop 0
	s_nop 0
	s_nop 0
	s_nop 0
	s_nop 0
	s_nop 0
	s_nop 0
	s_nop 0
	s_nop 0
	s_nop 0
	s_nop 0
	s_nop 0
	s_nop 0
	s_nop 0
	s_nop 0
	s_nop 0
	s_branch .LBB0_1688
